# adds: HGRN full-pass O+=AV / S+=KtV LDS fragment reads batched with counted lgkmcnt; early sample items per idle workgroup 6 -> 4 (stage 0 rebalanced after the faster state-only pass)
# speedup vs baseline: 1.0159x; 1.0041x over previous
.LBB0_302:
	v_writelane_b32 v253, s88, 24
	s_nop 1
	v_writelane_b32 v253, s89, 25
	v_writelane_b32 v253, s60, 26
	s_nop 1
	v_writelane_b32 v253, s61, 27
	v_writelane_b32 v253, s68, 28
	s_nop 1
	v_writelane_b32 v253, s69, 29
	s_or_b64 exec, exec, s[0:1]
	s_ashr_i32 s0, s90, 31
	s_add_u32 s30, s70, 0xd600000
	s_addc_u32 s31, s71, 0
	s_add_u32 s8, s70, 0x6700000
	s_addc_u32 s9, s71, 0
	s_add_u32 s6, s70, 0x8c00000
	s_addc_u32 s7, s71, 0
	s_add_u32 s14, s70, 0xb100000
	s_addc_u32 s15, s71, 0
	s_cmpk_lg_i32 s90, 0x100
	v_writelane_b32 v253, s0, 30
	s_cselect_b64 s[0:1], -1, 0
	v_writelane_b32 v253, s0, 31
	v_lshl_add_u64 v[2:3], v[2:3], 2, s[36:37]
	s_mov_b64 s[48:49], s[84:85]
	v_writelane_b32 v253, s1, 32
	s_mov_b64 s[50:51], s[86:87]
	v_readlane_b32 s10, v253, 0
	s_and_b32 s0, s10, 3
	s_cmp_eq_u32 s0, 3
	s_cselect_b64 s[0:1], -1, 0
	s_cmpk_eq_i32 s90, 0x100
	s_cselect_b64 s[12:13], -1, 0
	s_and_b64 s[2:3], s[12:13], exec
	s_cselect_b32 s4, 0x100, 0
	s_and_b64 s[0:1], s[0:1], s[12:13]
	s_ashr_i32 s5, s10, 2
	s_bitcmp1_b32 s10, 2
	s_cselect_b64 s[2:3], -1, 0
	v_writelane_b32 v253, s12, 33
	s_and_b64 s[2:3], s[2:3], s[12:13]
	s_and_b64 s[0:1], s[0:1], exec
	v_writelane_b32 v253, s13, 34
	s_cselect_b32 s0, s5, 0x1000
	v_writelane_b32 v253, s0, 35
	s_add_i32 s0, s4, s10
	s_cmpk_lt_i32 s10, 0x100
	v_writelane_b32 v253, s0, 36
	s_cselect_b64 s[0:1], -1, 0
	v_writelane_b32 v253, s0, 37
	s_cmpk_gt_i32 s10, 0xff
	s_mov_b64 s[36:37], s[72:73]
	v_writelane_b32 v253, s1, 38
	s_cselect_b64 s[0:1], -1, 0
	v_writelane_b32 v253, s0, 39
	s_mov_b64 s[42:43], s[78:79]
	s_mov_b64 s[46:47], s[82:83]
	v_writelane_b32 v253, s1, 40
	v_writelane_b32 v253, s2, 41
	s_xor_b64 s[0:1], s[2:3], -1
	s_waitcnt lgkmcnt(0)
	v_writelane_b32 v253, s3, 42
	v_writelane_b32 v253, s0, 43
	s_barrier
	s_nop 0
	v_writelane_b32 v253, s1, 44
	s_add_u32 s0, s70, 0x19846000
	v_writelane_b32 v253, s0, 45
	s_addc_u32 s0, s71, 0
	v_writelane_b32 v253, s0, 46
	s_add_u32 s0, s70, 0x1a846000
	s_addc_u32 s1, s71, 0
	v_writelane_b32 v253, s0, 47
	v_mov_b32_e32 v147, 0
	v_mov_b32_e32 v1, 0x358637bd
	v_writelane_b32 v253, s1, 48
	s_add_u32 s0, s86, 0x4800000
	v_writelane_b32 v253, s0, 49
	s_addc_u32 s0, s87, 0
	s_add_u32 s96, s70, 0x19842200
	s_addc_u32 s97, s71, 0
	v_writelane_b32 v253, s0, 50
	s_add_u32 s0, s70, 0x19842400
	s_addc_u32 s1, s71, 0
	v_writelane_b32 v253, s0, 51
	v_mov_b32_e32 v168, 1
	s_mov_b32 s33, 0x800000
	v_writelane_b32 v253, s1, 52
	s_add_u32 s0, s70, 0x19842500
	s_addc_u32 s1, s71, 0
	v_writelane_b32 v253, s0, 53
	s_movk_i32 s13, 0x110
	s_movk_i32 s18, 0x810
	v_writelane_b32 v253, s1, 54
	s_add_u32 s0, s70, 0x19842600
	s_addc_u32 s1, s71, 0
	v_writelane_b32 v253, s0, 55
	s_movk_i32 s25, 0x7fff
	s_mov_b64 s[16:17], -1
	v_writelane_b32 v253, s1, 56
	s_add_u32 s0, s70, 0x19842700
	s_addc_u32 s1, s71, 0
	v_writelane_b32 v253, s0, 57
	s_mov_b64 s[94:95], 0x10000
	s_nop 0
	v_writelane_b32 v253, s1, 58
	s_add_u32 s0, s70, 0x19842800
	s_addc_u32 s1, s71, 0
	v_writelane_b32 v253, s0, 59
	s_nop 1
	v_writelane_b32 v253, s1, 60
	s_add_u32 s0, s70, 0x19842900
	s_addc_u32 s1, s71, 0
	v_writelane_b32 v253, s0, 61
	s_nop 1
	v_writelane_b32 v253, s1, 62
	s_add_u32 s0, s70, 0x19842a00
	s_addc_u32 s1, s71, 0
	v_writelane_b32 v253, s0, 63
	s_nop 1
	v_writelane_b32 v254, s1, 0
	s_add_u32 s0, s70, 0x19842b00
	s_addc_u32 s1, s71, 0
	v_writelane_b32 v254, s0, 1
	s_nop 1
	v_writelane_b32 v254, s1, 2
	s_add_u32 s0, s70, 0x19842c00
	s_addc_u32 s1, s71, 0
	v_writelane_b32 v254, s0, 3
	s_nop 1
	v_writelane_b32 v254, s1, 4
	s_add_u32 s0, s70, 0x19842d00
	s_addc_u32 s1, s71, 0
	v_writelane_b32 v254, s0, 5
	s_nop 1
	v_writelane_b32 v254, s1, 6
	s_add_u32 s0, s70, 0x19842e00
	s_addc_u32 s1, s71, 0
	v_writelane_b32 v254, s0, 7
	s_nop 1
	v_writelane_b32 v254, s1, 8
	s_add_u32 s0, s70, 0x19842f00
	s_addc_u32 s1, s71, 0
	v_writelane_b32 v254, s0, 9
	s_nop 1
	v_writelane_b32 v254, s1, 10
	s_add_u32 s0, s70, 0x19843000
	s_addc_u32 s1, s71, 0
	v_writelane_b32 v254, s0, 11
	s_nop 1
	v_writelane_b32 v254, s1, 12
	s_add_u32 s0, s70, 0x19843100
	s_addc_u32 s1, s71, 0
	v_writelane_b32 v254, s0, 13
	s_nop 1
	v_writelane_b32 v254, s1, 14
	s_add_u32 s0, s70, 0x19843200
	s_addc_u32 s1, s71, 0
	v_writelane_b32 v254, s0, 15
	s_nop 1
	v_writelane_b32 v254, s1, 16
	s_add_u32 s0, s70, 0x19843300
	s_addc_u32 s1, s71, 0
	v_writelane_b32 v254, s0, 17
	s_cmp_eq_u32 s66, 15
	s_nop 0
	v_writelane_b32 v254, s1, 18
	s_cselect_b64 s[0:1], -1, 0
	v_writelane_b32 v254, s0, 19
	s_cmp_eq_u32 s66, 14
	s_nop 0
	v_writelane_b32 v254, s1, 20
	s_cselect_b64 s[0:1], -1, 0
	v_writelane_b32 v254, s0, 21
	s_cmp_eq_u32 s66, 13
	s_nop 0
	v_writelane_b32 v254, s1, 22
	s_cselect_b64 s[0:1], -1, 0
	v_writelane_b32 v254, s0, 23
	s_cmp_eq_u32 s66, 12
	s_nop 0
	v_writelane_b32 v254, s1, 24
	s_cselect_b64 s[0:1], -1, 0
	v_writelane_b32 v254, s0, 25
	s_cmp_eq_u32 s66, 11
	s_nop 0
	v_writelane_b32 v254, s1, 26
	s_cselect_b64 s[0:1], -1, 0
	v_writelane_b32 v254, s0, 27
	s_cmp_eq_u32 s66, 10
	s_nop 0
	v_writelane_b32 v254, s1, 28
	s_mov_b64 s[0:1], 0x1400
	v_lshl_add_u64 v[156:157], v[2:3], 0, s[0:1]
	s_mov_b64 s[0:1], 0x2400
	v_lshl_add_u64 v[154:155], v[2:3], 0, s[0:1]
	s_cselect_b64 s[0:1], -1, 0
	v_writelane_b32 v254, s0, 29
	s_cmp_eq_u32 s66, 9
	v_mbcnt_lo_u32_b32 v2, -1, 0
	v_writelane_b32 v254, s1, 30
	s_cselect_b64 s[0:1], -1, 0
	v_writelane_b32 v254, s0, 31
	s_cmp_eq_u32 s66, 8
	v_mbcnt_hi_u32_b32 v175, -1, v2
	v_writelane_b32 v254, s1, 32
	s_cselect_b64 s[0:1], -1, 0
	v_writelane_b32 v254, s0, 33
	s_cmp_eq_u32 s66, 7
	s_nop 0
	v_writelane_b32 v254, s1, 34
	s_cselect_b64 s[0:1], -1, 0
	v_writelane_b32 v254, s0, 35
	s_cmp_eq_u32 s66, 6
	s_nop 0
	v_writelane_b32 v254, s1, 36
	s_cselect_b64 s[0:1], -1, 0
	v_writelane_b32 v254, s0, 37
	s_cmp_eq_u32 s66, 5
	s_nop 0
	v_writelane_b32 v254, s1, 38
	s_cselect_b64 s[0:1], -1, 0
	v_writelane_b32 v254, s0, 39
	s_cmp_eq_u32 s66, 4
	s_nop 0
	v_writelane_b32 v254, s1, 40
	s_cselect_b64 s[0:1], -1, 0
	v_writelane_b32 v254, s0, 41
	s_cmp_eq_u32 s66, 3
	s_nop 0
	v_writelane_b32 v254, s1, 42
	s_cselect_b64 s[0:1], -1, 0
	v_writelane_b32 v254, s0, 43
	s_cmp_eq_u32 s66, 2
	s_nop 0
	v_writelane_b32 v254, s1, 44
	s_cselect_b64 s[0:1], -1, 0
	v_writelane_b32 v254, s0, 45
	s_cmp_eq_u32 s66, 1
	s_nop 0
	v_writelane_b32 v254, s1, 46
	s_cselect_b64 s[0:1], -1, 0
	v_writelane_b32 v254, s0, 47
	s_cmp_eq_u32 s66, 0
	s_nop 0
	v_writelane_b32 v254, s1, 48
	s_cselect_b64 s[0:1], -1, 0
	v_writelane_b32 v254, s0, 49
	s_nop 1
	v_writelane_b32 v254, s1, 50
	s_add_u32 s0, s70, 0x19845400
	s_addc_u32 s1, s71, 0
	v_writelane_b32 v254, s0, 51
	s_nop 1
	v_writelane_b32 v254, s1, 52
	s_add_u32 s0, s70, 0x19845500
	s_addc_u32 s1, s71, 0
	v_writelane_b32 v254, s0, 53
	s_nop 1
	v_writelane_b32 v254, s1, 54
	s_add_u32 s0, s86, 0x4c00000
	v_writelane_b32 v254, s0, 55
	s_addc_u32 s0, s87, 0
	v_writelane_b32 v254, s0, 56
	s_add_u32 s0, s70, 0x19846400
	v_writelane_b32 v254, s0, 57
	v_writelane_b32 v254, s70, 58
	s_addc_u32 s0, s71, 0
	s_nop 0
	v_writelane_b32 v254, s71, 59
	v_writelane_b32 v254, s0, 60
	s_add_i32 s0, 0, 0x13c00
	v_writelane_b32 v254, s0, 61
	s_add_i32 s0, 0, 0x1c600
	v_writelane_b32 v254, s0, 62
	s_add_i32 s0, 0, 0x1c400
	v_writelane_b32 v254, s0, 63
	s_add_i32 s0, 0, 0x11800
	v_writelane_b32 v255, s0, 0
	s_add_i32 s0, 0, 0x20000
	v_writelane_b32 v255, s0, 1
	s_add_i32 s0, 0, 0x20004
	v_writelane_b32 v255, s0, 2
	v_writelane_b32 v255, s36, 3
	v_readlane_b32 s56, v253, 5
	v_readlane_b32 s57, v253, 6
	v_writelane_b32 v255, s37, 4
	v_writelane_b32 v255, s38, 5
	v_writelane_b32 v255, s39, 6
	v_writelane_b32 v255, s40, 7
	v_writelane_b32 v255, s41, 8
	v_writelane_b32 v255, s42, 9
	v_writelane_b32 v255, s43, 10
	v_writelane_b32 v255, s44, 11
	v_writelane_b32 v255, s45, 12
	v_writelane_b32 v255, s46, 13
	v_writelane_b32 v255, s47, 14
	v_writelane_b32 v255, s48, 15
	v_writelane_b32 v255, s49, 16
	v_writelane_b32 v255, s50, 17
	v_writelane_b32 v255, s51, 18
	v_writelane_b32 v255, s90, 19
	v_writelane_b32 v255, s96, 20
	v_readlane_b32 s58, v253, 7
	v_readlane_b32 s59, v253, 8
	v_readlane_b32 s60, v253, 9
	v_readlane_b32 s61, v253, 10
	v_readlane_b32 s62, v253, 11
	v_readlane_b32 s63, v253, 12
	v_readlane_b32 s64, v253, 13
	v_readlane_b32 s65, v253, 14
	v_readlane_b32 s66, v253, 15
	v_readlane_b32 s67, v253, 16
	v_readlane_b32 s68, v253, 17
	v_readlane_b32 s69, v253, 18
	v_readlane_b32 s70, v253, 19
	v_readlane_b32 s71, v253, 20
	v_writelane_b32 v255, s97, 21
	s_branch .LBB0_306

.LBB0_306:
	s_xor_b64 s[96:97], s[16:17], -1
	s_and_b64 s[0:1], s[16:17], exec
	v_readlane_b32 s0, v253, 35
	v_readlane_b32 s1, v253, 36
	s_cselect_b32 s4, s0, s1
	s_movk_i32 s0, 0x800
	s_cselect_b32 s26, 0x100, s0
	s_cselect_b32 s20, 64, s90
	s_cmp_lt_i32 s4, s26
	s_cselect_b64 s[0:1], -1, 0
	v_writelane_b32 v255, s0, 22
	s_lshl_b32 s2, s4, 7
	s_mov_b64 s[22:23], -1
	v_writelane_b32 v255, s1, 23
	s_ashr_i32 s0, s4, 1
	s_and_b32 s0, s0, -8
	s_ashr_i32 s1, s0, 31
	s_lshl_b64 s[0:1], s[0:1], 11
	v_writelane_b32 v255, s2, 24
	s_and_b32 s2, s2, 0x780
	s_or_b32 s0, s0, s2
	s_add_u32 s0, s0, 0x1020000
	v_writelane_b32 v255, s0, 25
	s_addc_u32 s0, s1, 0
	v_writelane_b32 v255, s0, 26
	s_mov_b32 s0, s4
	s_ashr_i32 s5, s4, 31
	v_writelane_b32 v255, s0, 27
	s_nop 1
	v_writelane_b32 v255, s1, 28
	s_lshl_b64 s[0:1], s[4:5], 16
	s_add_u32 s2, s60, s0
	s_addc_u32 s3, s61, s1
	v_writelane_b32 v255, s2, 29
	s_nop 1
	v_writelane_b32 v255, s3, 30
	s_and_b64 s[2:3], s[16:17], exec
	v_readlane_b32 s2, v253, 46
	v_readlane_b32 s3, v253, 50
	s_cselect_b32 s2, s2, s3
	v_writelane_b32 v255, s2, 31
	v_readlane_b32 s2, v253, 45
	v_readlane_b32 s3, v253, 49
	s_cselect_b32 s2, s2, s3
	v_writelane_b32 v255, s2, 32
	v_readlane_b32 s2, v254, 55
	s_add_u32 s2, s2, s0
	v_readlane_b32 s0, v254, 56
	s_addc_u32 s3, s0, s1
	v_writelane_b32 v255, s2, 33
	s_ashr_i32 s21, s20, 31
	v_readlane_b32 s0, v253, 43
	v_writelane_b32 v255, s3, 34
	s_lshl_b64 s[34:35], s[20:21], 16
	s_lshl_b32 s21, s20, 7
	v_readlane_b32 s1, v253, 44

.LBB0_431:
	s_or_b64 exec, exec, vcc
	s_nop 6
	v_cndmask_b32_e64 v38, v130, 0, s[54:55]
	v_bfe_u32 v39, v38, 16, 1
	v_add3_u32 v38, v38, v39, s25
	ds_write_b16_d16_hi v183, v38
	v_cndmask_b32_e64 v38, v131, 0, s[56:57]
	v_bfe_u32 v39, v38, 16, 1
	v_add3_u32 v38, v38, v39, s25
	ds_write_b16_d16_hi v183, v38 offset:144
	v_cndmask_b32_e64 v38, v132, 0, s[58:59]
	v_bfe_u32 v39, v38, 16, 1
	v_add3_u32 v38, v38, v39, s25
	ds_write_b16_d16_hi v183, v38 offset:288
	v_cndmask_b32_e64 v38, v133, 0, s[60:61]
	v_bfe_u32 v39, v38, 16, 1
	v_add3_u32 v38, v38, v39, s25
	ds_write_b16_d16_hi v183, v38 offset:432
	s_waitcnt lgkmcnt(0)
	s_barrier
	v_add_u32_e32 v243, v167, v165
	v_add_u32_e32 v252, v166, v176
	s_mov_b64 s[10:11], 0
	ds_read_b128 v[244:247], v184
	ds_read_b128 v[130:133], v185 offset:53248
	ds_read_b128 v[134:137], v185 offset:55552
	ds_read_b128 v[138:141], v185 offset:57856
	ds_read_b128 v[142:145], v185 offset:60160
	ds_read_b128 v[248:251], v184 offset:64
	ds_read_b128 v[38:41], v185 offset:53312
	ds_read_b128 v[42:45], v185 offset:55616
	ds_read_b128 v[46:49], v185 offset:57920
	ds_read_b128 v[50:53], v185 offset:60224
	s_waitcnt lgkmcnt(8)
	v_mfma_f32_16x16x32_bf16 v[34:37], v[244:247], v[130:133], v[34:37]
	s_waitcnt lgkmcnt(7)
	v_mfma_f32_16x16x32_bf16 v[54:57], v[244:247], v[134:137], v[54:57]
	s_waitcnt lgkmcnt(6)
	v_mfma_f32_16x16x32_bf16 v[58:61], v[244:247], v[138:141], v[58:61]
	s_waitcnt lgkmcnt(5)
	v_mfma_f32_16x16x32_bf16 v[62:65], v[244:247], v[142:145], v[62:65]
	ds_read_b128 v[244:247], v243 offset:34816
	s_waitcnt lgkmcnt(4)
	v_mfma_f32_16x16x32_bf16 v[130:133], v[248:251], v[38:41], v[34:37]
	ds_read_b128 v[38:41], v252 offset:53248
	s_waitcnt lgkmcnt(4)
	v_mfma_f32_16x16x32_bf16 v[134:137], v[248:251], v[42:45], v[54:57]
	ds_read_b128 v[42:45], v252 offset:55552
	s_waitcnt lgkmcnt(4)
	v_mfma_f32_16x16x32_bf16 v[138:141], v[248:251], v[46:49], v[58:61]
	ds_read_b128 v[46:49], v252 offset:57856
	s_waitcnt lgkmcnt(4)
	v_mfma_f32_16x16x32_bf16 v[142:145], v[248:251], v[50:53], v[62:65]
	ds_read_b128 v[50:53], v252 offset:60160
	ds_read_b128 v[248:251], v243 offset:34880
	ds_read_b128 v[34:37], v252 offset:62464
	ds_read_b128 v[54:57], v252 offset:64768
	ds_read_b128 v[58:61], v186 offset:64768
	ds_read_b128 v[62:65], v187 offset:64768
	s_waitcnt lgkmcnt(8)
	v_mfma_f32_16x16x32_bf16 v[2:5], v[244:247], v[38:41], v[2:5]
	ds_read_b128 v[38:41], v252 offset:53312
	s_waitcnt lgkmcnt(8)
	v_mfma_f32_16x16x32_bf16 v[6:9], v[244:247], v[42:45], v[6:9]
	ds_read_b128 v[42:45], v252 offset:55616
	s_waitcnt lgkmcnt(8)
	v_mfma_f32_16x16x32_bf16 v[10:13], v[244:247], v[46:49], v[10:13]
	ds_read_b128 v[46:49], v252 offset:57920
	s_waitcnt lgkmcnt(8)
	v_mfma_f32_16x16x32_bf16 v[14:17], v[244:247], v[50:53], v[14:17]
	ds_read_b128 v[50:53], v252 offset:60224
	s_waitcnt lgkmcnt(7)
	v_mfma_f32_16x16x32_bf16 v[18:21], v[244:247], v[34:37], v[18:21]
	ds_read_b128 v[34:37], v252 offset:62528
	s_waitcnt lgkmcnt(7)
	v_mfma_f32_16x16x32_bf16 v[22:25], v[244:247], v[54:57], v[22:25]
	ds_read_b128 v[54:57], v252 offset:64832
	s_waitcnt lgkmcnt(7)
	v_mfma_f32_16x16x32_bf16 v[26:29], v[244:247], v[58:61], v[26:29]
	ds_read_b128 v[58:61], v186 offset:64832
	s_waitcnt lgkmcnt(7)
	v_mfma_f32_16x16x32_bf16 v[30:33], v[244:247], v[62:65], v[30:33]
	ds_read_b128 v[62:65], v187 offset:64832
	s_waitcnt lgkmcnt(7)
	v_mfma_f32_16x16x32_bf16 v[2:5], v[248:251], v[38:41], v[2:5]
	s_waitcnt lgkmcnt(6)
	v_mfma_f32_16x16x32_bf16 v[6:9], v[248:251], v[42:45], v[6:9]
	s_waitcnt lgkmcnt(5)
	v_mfma_f32_16x16x32_bf16 v[10:13], v[248:251], v[46:49], v[10:13]
	s_waitcnt lgkmcnt(4)
	v_mfma_f32_16x16x32_bf16 v[14:17], v[248:251], v[50:53], v[14:17]
	s_waitcnt lgkmcnt(3)
	v_mfma_f32_16x16x32_bf16 v[18:21], v[248:251], v[34:37], v[18:21]
	s_waitcnt lgkmcnt(2)
	v_mfma_f32_16x16x32_bf16 v[22:25], v[248:251], v[54:57], v[22:25]
	s_waitcnt lgkmcnt(1)
	v_mfma_f32_16x16x32_bf16 v[26:29], v[248:251], v[58:61], v[26:29]
	s_waitcnt lgkmcnt(0)
	v_mfma_f32_16x16x32_bf16 v[30:33], v[248:251], v[62:65], v[30:33]
	v_pk_mul_f32 v[34:35], v[122:123], v[2:3]
	v_mul_f32_e64 v36, v124, v4
	v_mul_f32_e64 v37, v125, v5
	v_pk_mul_f32 v[38:39], v[122:123], v[6:7]
	v_pk_mul_f32 v[40:41], v[124:125], v[8:9]
	v_pk_mul_f32 v[42:43], v[122:123], v[10:11]
	v_pk_mul_f32 v[44:45], v[124:125], v[12:13]
	v_pk_mul_f32 v[46:47], v[122:123], v[14:15]
	v_pk_mul_f32 v[48:49], v[124:125], v[16:17]
	v_pk_mul_f32 v[50:51], v[122:123], v[18:19]
	v_pk_mul_f32 v[52:53], v[124:125], v[20:21]
	v_pk_mul_f32 v[54:55], v[122:123], v[22:23]
	v_pk_mul_f32 v[56:57], v[124:125], v[24:25]
	v_pk_mul_f32 v[58:59], v[122:123], v[26:27]
	v_pk_mul_f32 v[60:61], v[124:125], v[28:29]
	v_pk_mul_f32 v[62:63], v[122:123], v[30:31]
	v_pk_mul_f32 v[64:65], v[124:125], v[32:33]
	v_cvt_pk_bf16_f32 v244, v34, v35
	v_cvt_pk_bf16_f32 v245, v36, v37
	ds_write_b64 v188, v[244:245]
	v_cvt_pk_bf16_f32 v246, v38, v39
	v_cvt_pk_bf16_f32 v247, v40, v41
	ds_write_b64 v188, v[246:247] offset:4352
	v_cvt_pk_bf16_f32 v248, v42, v43
	v_cvt_pk_bf16_f32 v249, v44, v45
	ds_write_b64 v188, v[248:249] offset:8704
	v_cvt_pk_bf16_f32 v250, v46, v47
	v_cvt_pk_bf16_f32 v251, v48, v49
	ds_write_b64 v188, v[250:251] offset:13056
	v_cvt_pk_bf16_f32 v244, v50, v51
	v_cvt_pk_bf16_f32 v245, v52, v53
	ds_write_b64 v188, v[244:245] offset:17408
	v_cvt_pk_bf16_f32 v246, v54, v55
	v_cvt_pk_bf16_f32 v247, v56, v57
	ds_write_b64 v188, v[246:247] offset:21760
	v_cvt_pk_bf16_f32 v248, v58, v59
	v_cvt_pk_bf16_f32 v249, v60, v61
	ds_write_b64 v188, v[248:249] offset:26112
	v_cvt_pk_bf16_f32 v250, v62, v63
	v_cvt_pk_bf16_f32 v251, v64, v65
	ds_write_b64 v188, v[250:251] offset:30464
	ds_write2_b32 v189, v130, v134 offset1:16
	ds_write2_b32 v189, v131, v135 offset0:132 offset1:148
	v_add_u32_e32 v130, 0x400, v189
	ds_write2_b32 v130, v132, v136 offset0:8 offset1:24
	ds_write2_b32 v130, v133, v137 offset0:140 offset1:156
	ds_write2_b32 v189, v138, v142 offset0:32 offset1:48
	ds_write2_b32 v189, v139, v143 offset0:164 offset1:180
	ds_write2_b32 v130, v140, v144 offset0:40 offset1:56
	ds_write2_b32 v130, v141, v145 offset0:172 offset1:188
	s_waitcnt lgkmcnt(0)
	s_barrier
	ds_read_b128 v[130:133], v190
	ds_read_b128 v[134:137], v190 offset:16
	ds_read_b128 v[138:141], v190 offset:32
	ds_read_b128 v[142:145], v190 offset:48
	s_waitcnt lgkmcnt(3)
	v_pk_mul_f32 v[244:245], v[132:133], v[132:133]
	v_pk_mul_f32 v[246:247], v[130:131], v[130:131]
	s_waitcnt lgkmcnt(0)
	v_mul_f32_e32 v243, v142, v142
	v_pk_mov_b32 v[248:249], v[246:247], v[244:245] op_sel:[1,0]
	v_mov_b32_e32 v247, v245
	v_pk_add_f32 v[244:245], v[248:249], v[246:247]
	v_pk_mul_f32 v[246:247], v[136:137], v[136:137]
	v_pk_mul_f32 v[248:249], v[134:135], v[134:135]
	v_pk_add_f32 v[244:245], v[244:245], v[244:245] op_sel:[0,1] op_sel_hi:[1,0]
	v_pk_mov_b32 v[250:251], v[248:249], v[246:247] op_sel:[1,0]
	v_mov_b32_e32 v249, v247
	v_pk_add_f32 v[246:247], v[250:251], v[248:249]
	v_mul_f32_e32 v248, v143, v143
	v_pk_add_f32 v[246:247], v[246:247], v[246:247] op_sel:[0,1] op_sel_hi:[1,0]
	v_mov_b32_e32 v245, v243
	v_mov_b32_e32 v247, v248
	v_pk_add_f32 v[244:245], v[244:245], v[246:247]
	v_mul_f32_e32 v246, v139, v139
	v_mul_f32_e32 v249, v144, v144
	v_pk_fma_f32 v[246:247], v[138:139], v[138:139], v[246:247] op_sel_hi:[1,1,0]
	v_mul_f32_e32 v248, v141, v141
	v_mul_f32_e32 v250, v145, v145
	v_mov_b32_e32 v247, v249
	v_pk_fma_f32 v[248:249], v[140:141], v[140:141], v[248:249] op_sel_hi:[1,1,0]
	s_nop 0
	v_mov_b32_e32 v249, v250
	v_pk_add_f32 v[246:247], v[246:247], v[248:249]
	s_nop 0
	v_pk_add_f32 v[244:245], v[244:245], v[246:247]
	s_nop 0
	v_add_f32_e32 v243, v244, v245
	v_and_b32_e32 v245, 64, v175
	v_xor_b32_e32 v244, 1, v175
	v_add_u32_e32 v245, 64, v245
	v_cmp_lt_i32_e32 vcc, v244, v245
	s_nop 1
	v_cndmask_b32_e32 v244, v175, v244, vcc
	v_lshlrev_b32_e32 v244, 2, v244
	ds_bpermute_b32 v244, v244, v243
	s_waitcnt lgkmcnt(0)
	v_add_f32_e32 v243, v243, v244
	v_xor_b32_e32 v244, 2, v175
	v_cmp_lt_i32_e32 vcc, v244, v245
	s_nop 1
	v_cndmask_b32_e32 v244, v175, v244, vcc
	v_lshlrev_b32_e32 v244, 2, v244
	ds_bpermute_b32 v244, v244, v243
	s_waitcnt lgkmcnt(0)
	v_add_f32_e32 v243, v243, v244
	v_xor_b32_e32 v244, 4, v175
	v_cmp_lt_i32_e32 vcc, v244, v245
	s_nop 1
	v_cndmask_b32_e32 v244, v175, v244, vcc
	v_lshlrev_b32_e32 v244, 2, v244
	ds_bpermute_b32 v244, v244, v243
	s_waitcnt lgkmcnt(0)
	v_add_f32_e32 v243, v243, v244
	v_fmamk_f32 v243, v243, 0x3c000000, v1
	v_cmp_gt_f32_e32 vcc, s33, v243
	v_mul_f32_e32 v244, 0x4b800000, v243
	s_nop 0
	v_cndmask_b32_e32 v243, v243, v244, vcc
	v_rsq_f32_e32 v243, v243
	s_nop 0
	v_mul_f32_e32 v244, 0x45800000, v243
	v_cndmask_b32_e32 v243, v243, v244, vcc
	v_mul_f32_e32 v131, v131, v243
	s_waitcnt vmcnt(0)
	v_lshlrev_b32_e32 v244, 16, v126
	v_mul_f32_e32 v131, v111, v131
	v_and_b32_e32 v126, 0xffff0000, v126
	v_mul_f32_e32 v126, v131, v126
	v_mul_f32_e32 v131, v132, v243
	v_mul_f32_e32 v130, v130, v243
	v_mul_f32_e32 v131, v112, v131
	v_lshlrev_b32_e32 v132, 16, v127
	v_mul_f32_e32 v130, v110, v130
	v_mul_f32_e32 v131, v131, v132
	v_mul_f32_e32 v132, v133, v243
	v_mul_f32_e32 v130, v130, v244
	v_mul_f32_e32 v132, v113, v132
	v_and_b32_e32 v127, 0xffff0000, v127
	v_mul_f32_e32 v127, v132, v127
	v_cvt_pk_bf16_f32 v126, v130, v126
	v_mul_f32_e32 v130, v134, v243
	v_cvt_pk_bf16_f32 v127, v131, v127
	v_mul_f32_e32 v130, v106, v130
	v_lshlrev_b32_e32 v131, 16, v128
	v_mul_f32_e32 v130, v130, v131
	v_mul_f32_e32 v131, v135, v243
	v_mul_f32_e32 v131, v107, v131
	v_and_b32_e32 v128, 0xffff0000, v128
	v_mul_f32_e32 v128, v131, v128
	v_mul_f32_e32 v131, v136, v243
	v_mul_f32_e32 v131, v108, v131
	v_lshlrev_b32_e32 v132, 16, v129
	v_mul_f32_e32 v131, v131, v132
	v_mul_f32_e32 v132, v137, v243
	v_mul_f32_e32 v132, v109, v132
	v_and_b32_e32 v129, 0xffff0000, v129
	v_mul_f32_e32 v129, v132, v129
	v_cvt_pk_bf16_f32 v128, v130, v128
	v_mul_f32_e32 v130, v138, v243
	v_cvt_pk_bf16_f32 v129, v131, v129
	v_mul_f32_e32 v130, v102, v130
	v_lshlrev_b32_e32 v131, 16, v118
	v_mul_f32_e32 v130, v130, v131
	v_mul_f32_e32 v131, v139, v243
	v_mul_f32_e32 v131, v103, v131
	v_and_b32_e32 v118, 0xffff0000, v118
	v_mul_f32_e32 v118, v131, v118
	v_mul_f32_e32 v131, v140, v243
	v_mul_f32_e32 v131, v104, v131
	v_lshlrev_b32_e32 v132, 16, v119
	v_mul_f32_e32 v131, v131, v132
	v_mul_f32_e32 v132, v141, v243
	v_mul_f32_e32 v132, v105, v132
	v_and_b32_e32 v119, 0xffff0000, v119
	v_mul_f32_e32 v119, v132, v119
	v_cvt_pk_bf16_f32 v118, v130, v118
	v_mul_f32_e32 v130, v142, v243
	v_cvt_pk_bf16_f32 v119, v131, v119
	v_mul_f32_e32 v130, v98, v130
	v_lshlrev_b32_e32 v131, 16, v120
	v_mul_f32_e32 v130, v130, v131
	v_mul_f32_e32 v131, v143, v243
	v_mul_f32_e32 v131, v99, v131
	v_and_b32_e32 v120, 0xffff0000, v120
	v_mul_f32_e32 v120, v131, v120
	v_mul_f32_e32 v131, v144, v243
	v_mul_f32_e32 v131, v100, v131
	v_lshlrev_b32_e32 v132, 16, v121
	v_mul_f32_e32 v131, v131, v132
	v_mul_f32_e32 v132, v145, v243
	v_mul_f32_e32 v132, v101, v132
	v_and_b32_e32 v121, 0xffff0000, v121
	v_mul_f32_e32 v121, v132, v121
	v_cvt_pk_bf16_f32 v120, v130, v120
	v_cvt_pk_bf16_f32 v121, v131, v121
	v_lshl_add_u64 v[130:131], v[152:153], 1, s[30:31]
	global_store_dwordx4 v[130:131], v[126:129], off
	global_store_dwordx4 v[130:131], v[118:121], off offset:16
